# barrier-poll back-off: s_sleep 1 -> s_sleep 8 in all 34 grid-barrier spin loops, on top of v12
# baseline (speedup 1.0000x reference)
; __global__ void __launch_bounds__(NT, 2) fwd_megakernel(Params p) {
;     ...
;     grid.sync();
.LBB0_252:
	s_sleep 8
	global_load_dword v2, v0, s[2:3] offset:32 sc1
	s_waitcnt vmcnt(0)
	v_and_b32_e32 v2, 0xffff0000, v2
	v_cmp_ne_u32_e32 vcc, v2, v1
	s_or_b64 s[6:7], vcc, s[6:7]
	s_andn2_b64 exec, exec, s[6:7]
	s_cbranch_execnz .LBB0_252

; __device__ __forceinline__ unsigned xb_ld(unsigned* p)              { return __hip_atomic_load(p, __ATOMIC_RELAXED, __HIP_MEMORY_SCOPE_AGENT); }
; __device__ __forceinline__ void xcd_barrier_complete(unsigned* bar, unsigned x, unsigned& nloc, unsigned& nx) {
;     const unsigned G = gridDim.x * gridDim.y * gridDim.z;
;     unsigned sum, cnt, mine, sp = 0u;
;     for (;;) {
;         sum = 0u; cnt = 0u; mine = 0u;
; #pragma unroll
;         for (unsigned j = 0; j < 16; ++j) { const unsigned c = xb_ld(&bar[XB_XCNT(j)]); sum += c; cnt += (c > 0u) ? 1u : 0u; mine = (j == x) ? c : mine; }
;         if (sum == G) break;
;         __builtin_amdgcn_s_sleep(1);
;         if ((++sp & 255u) == 0u) { if (xb_ld(&bar[XB_TMO])) break; if (sp > XB_SPIN_CAP) { atomicAdd(&bar[XB_TMO], 1u); break; } }
;     }
.LBB0_266:
	flat_load_dword v25, v[0:1] offset:1024 sc1
	flat_load_dword v10, v[0:1] offset:1280 sc1
	flat_load_dword v11, v[0:1] offset:1536 sc1
	flat_load_dword v12, v[0:1] offset:1792 sc1
	flat_load_dword v13, v[0:1] offset:2048 sc1
	flat_load_dword v14, v[0:1] offset:2304 sc1
	flat_load_dword v15, v[0:1] offset:2560 sc1
	flat_load_dword v16, v[0:1] offset:2816 sc1
	flat_load_dword v17, v[0:1] offset:3072 sc1
	flat_load_dword v18, v[0:1] offset:3328 sc1
	flat_load_dword v19, v[0:1] offset:3584 sc1
	flat_load_dword v20, v[0:1] offset:3840 sc1
	flat_load_dword v21, v[2:3] sc1
	flat_load_dword v22, v[4:5] sc1
	flat_load_dword v23, v[6:7] sc1
	flat_load_dword v24, v[8:9] sc1
	s_or_b64 s[8:9], s[8:9], exec
	s_or_b64 s[6:7], s[6:7], exec
	s_waitcnt vmcnt(0) lgkmcnt(0)
	v_add_u32_e32 v26, v10, v25
	v_add_u32_e32 v26, v26, v11
	v_add_u32_e32 v26, v26, v12
	v_add_u32_e32 v26, v26, v13
	v_add_u32_e32 v26, v26, v14
	v_add_u32_e32 v26, v26, v15
	v_add_u32_e32 v26, v26, v16
	v_add_u32_e32 v26, v26, v17
	v_add_u32_e32 v26, v26, v18
	v_add_u32_e32 v26, v26, v19
	v_add_u32_e32 v26, v26, v20
	v_add_u32_e32 v26, v26, v21
	v_add_u32_e32 v26, v26, v22
	v_add_u32_e32 v26, v26, v23
	v_add_u32_e32 v26, v26, v24
	v_cmp_ne_u32_e32 vcc, s20, v26
	s_and_saveexec_b64 s[10:11], vcc
	s_cbranch_execz .LBB0_265
	s_and_b32 s14, s21, 0xff
	s_mov_b64 s[12:13], -1
	s_cmp_eq_u32 s14, 0
	s_mov_b64 s[16:17], -1
	s_mov_b64 s[14:15], -1
	s_sleep 8
	s_cbranch_scc1 .LBB0_269
	s_and_saveexec_b64 s[18:19], s[16:17]
	s_cbranch_execz .LBB0_264
	s_branch .LBB0_272

; __device__ __forceinline__ unsigned xb_ld(unsigned* p)              { return __hip_atomic_load(p, __ATOMIC_RELAXED, __HIP_MEMORY_SCOPE_AGENT); }
; __device__ __forceinline__ unsigned xb_add(unsigned* p, unsigned v) { return __hip_atomic_fetch_add(p, v, __ATOMIC_RELAXED, __HIP_MEMORY_SCOPE_AGENT); }
; #define XB_SPIN(cond, bar) do { unsigned _sp = 0; while (cond) { __builtin_amdgcn_s_sleep(1); \
;     if ((++_sp & 255u) == 0u) { if (xb_ld(&(bar)[XB_TMO])) break; if (_sp > XB_SPIN_CAP) { atomicAdd(&(bar)[XB_TMO], 1u); break; } } } } while (0)
; __device__ __forceinline__ void xcd_barrier(const XcdBarrier& b) {
;     ...
;             else XB_SPIN(xb_ld(&bar[XB_TOPGEN]) == tg, bar);
;             __builtin_amdgcn_fence(__ATOMIC_ACQUIRE, "agent");
;             xb_add(&bar[XB_XGEN(b.x)], 1u);
;             asm volatile("s_waitcnt vmcnt(0)" ::: "memory");
;         } else {
;             XB_SPIN(xb_ld(&bar[XB_XGEN(b.x)]) == gen, bar);
.LBB0_280:
	s_and_b32 s16, s24, 0xff
	s_mov_b64 s[14:15], -1
	s_cmp_lg_u32 s16, 0
	s_mov_b64 s[16:17], -1
	s_sleep 8
	s_cbranch_scc1 .LBB0_284
	v_mov_b64_e32 v[2:3], s[34:35]
	flat_load_dword v0, v[2:3] offset:512 sc1
	s_mov_b64 s[16:17], 0
	s_mov_b64 s[18:19], -1
	s_waitcnt vmcnt(0) lgkmcnt(0)
	v_cmp_eq_u32_e32 vcc, 0, v0
	s_and_saveexec_b64 s[20:21], vcc
	s_cmp_lt_u32 s24, 0x40001
	s_cselect_b64 s[16:17], -1, 0
	s_xor_b64 s[18:19], exec, -1
	s_and_b64 s[16:17], s[16:17], exec
	s_or_b64 exec, exec, s[20:21]

; __device__ __forceinline__ unsigned xb_ld(unsigned* p)              { return __hip_atomic_load(p, __ATOMIC_RELAXED, __HIP_MEMORY_SCOPE_AGENT); }
; __device__ __forceinline__ unsigned xb_add(unsigned* p, unsigned v) { return __hip_atomic_fetch_add(p, v, __ATOMIC_RELAXED, __HIP_MEMORY_SCOPE_AGENT); }
; #define XB_SPIN(cond, bar) do { unsigned _sp = 0; while (cond) { __builtin_amdgcn_s_sleep(1); \
;     if ((++_sp & 255u) == 0u) { if (xb_ld(&(bar)[XB_TMO])) break; if (_sp > XB_SPIN_CAP) { atomicAdd(&(bar)[XB_TMO], 1u); break; } } } } while (0)
; __device__ __forceinline__ void xcd_barrier(const XcdBarrier& b) {
;     ...
;             else XB_SPIN(xb_ld(&bar[XB_TOPGEN]) == tg, bar);
;             __builtin_amdgcn_fence(__ATOMIC_ACQUIRE, "agent");
;             xb_add(&bar[XB_XGEN(b.x)], 1u);
;             asm volatile("s_waitcnt vmcnt(0)" ::: "memory");
;         } else {
;             XB_SPIN(xb_ld(&bar[XB_XGEN(b.x)]) == gen, bar);
.LBB0_294:
	s_and_b32 s14, s24, 0xff
	s_cmp_lg_u32 s14, 0
	s_mov_b64 s[16:17], -1
	s_sleep 8
	s_cbranch_scc0 .LBB0_296
	s_mov_b64 s[18:19], -1
	s_and_saveexec_b64 s[20:21], s[16:17]
	s_cbranch_execz .LBB0_293
	s_branch .LBB0_299

; __device__ __forceinline__ unsigned xb_ld(unsigned* p)              { return __hip_atomic_load(p, __ATOMIC_RELAXED, __HIP_MEMORY_SCOPE_AGENT); }
; __device__ __forceinline__ void xcd_barrier_complete(unsigned* bar, unsigned x, unsigned& nloc, unsigned& nx) {
;     const unsigned G = gridDim.x * gridDim.y * gridDim.z;
;     unsigned sum, cnt, mine, sp = 0u;
;     for (;;) {
;         sum = 0u; cnt = 0u; mine = 0u;
; #pragma unroll
;         for (unsigned j = 0; j < 16; ++j) { const unsigned c = xb_ld(&bar[XB_XCNT(j)]); sum += c; cnt += (c > 0u) ? 1u : 0u; mine = (j == x) ? c : mine; }
;         if (sum == G) break;
;         __builtin_amdgcn_s_sleep(1);
;         if ((++sp & 255u) == 0u) { if (xb_ld(&bar[XB_TMO])) break; if (sp > XB_SPIN_CAP) { atomicAdd(&bar[XB_TMO], 1u); break; } }
;     }
.LBB0_335:
	v_mov_b64_e32 v[14:15], s[34:35]
	flat_load_dword v12, v[14:15] offset:1024 sc1
	s_waitcnt lgkmcnt(0)
	flat_load_dword v0, v[14:15] offset:1280 sc1
	flat_load_dword v2, v[14:15] offset:1536 sc1
	flat_load_dword v3, v[14:15] offset:1792 sc1
	flat_load_dword v4, v[14:15] offset:2048 sc1
	flat_load_dword v5, v[14:15] offset:2304 sc1
	flat_load_dword v6, v[14:15] offset:2560 sc1
	flat_load_dword v7, v[14:15] offset:2816 sc1
	flat_load_dword v8, v[14:15] offset:3072 sc1
	flat_load_dword v9, v[14:15] offset:3328 sc1
	flat_load_dword v10, v[14:15] offset:3584 sc1
	flat_load_dword v11, v[14:15] offset:3840 sc1
	v_mov_b64_e32 v[14:15], s[0:1]
	flat_load_dword v13, v[14:15] sc1
	v_mov_b64_e32 v[14:15], s[4:5]
	flat_load_dword v14, v[14:15] sc1
	v_mov_b64_e32 v[16:17], s[6:7]
	flat_load_dword v15, v[16:17] sc1
	v_mov_b64_e32 v[16:17], s[8:9]
	flat_load_dword v16, v[16:17] sc1
	v_readlane_b32 s18, v253, 57
	s_or_b64 s[16:17], s[16:17], exec
	s_or_b64 s[14:15], s[14:15], exec
	s_waitcnt vmcnt(0) lgkmcnt(0)
	v_add_u32_e32 v17, v0, v12
	v_add_u32_e32 v17, v17, v2
	v_add_u32_e32 v17, v17, v3
	v_add_u32_e32 v17, v17, v4
	v_add_u32_e32 v17, v17, v5
	v_add_u32_e32 v17, v17, v6
	v_add_u32_e32 v17, v17, v7
	v_add_u32_e32 v17, v17, v8
	v_add_u32_e32 v17, v17, v9
	v_add_u32_e32 v17, v17, v10
	v_add_u32_e32 v17, v17, v11
	v_add_u32_e32 v17, v17, v13
	v_add_u32_e32 v17, v17, v14
	v_add_u32_e32 v17, v17, v15
	v_add_u32_e32 v17, v17, v16
	v_cmp_ne_u32_e32 vcc, s18, v17
	s_and_saveexec_b64 s[18:19], vcc
	s_cbranch_execz .LBB0_334
	s_and_b32 s22, s28, 0xff
	s_mov_b64 s[20:21], -1
	s_cmp_eq_u32 s22, 0
	s_mov_b64 s[24:25], -1
	s_mov_b64 s[22:23], -1
	s_sleep 8
	s_cbranch_scc1 .LBB0_338
	s_and_saveexec_b64 s[26:27], s[24:25]
	s_cbranch_execz .LBB0_333
	s_branch .LBB0_341

; __device__ __forceinline__ unsigned xb_ld(unsigned* p)              { return __hip_atomic_load(p, __ATOMIC_RELAXED, __HIP_MEMORY_SCOPE_AGENT); }
; __device__ __forceinline__ unsigned xb_add(unsigned* p, unsigned v) { return __hip_atomic_fetch_add(p, v, __ATOMIC_RELAXED, __HIP_MEMORY_SCOPE_AGENT); }
; #define XB_SPIN(cond, bar) do { unsigned _sp = 0; while (cond) { __builtin_amdgcn_s_sleep(1); \
;     if ((++_sp & 255u) == 0u) { if (xb_ld(&(bar)[XB_TMO])) break; if (_sp > XB_SPIN_CAP) { atomicAdd(&(bar)[XB_TMO], 1u); break; } } } } while (0)
; __device__ __forceinline__ void xcd_barrier(const XcdBarrier& b) {
;     ...
;             else XB_SPIN(xb_ld(&bar[XB_TOPGEN]) == tg, bar);
;             __builtin_amdgcn_fence(__ATOMIC_ACQUIRE, "agent");
;             xb_add(&bar[XB_XGEN(b.x)], 1u);
;             asm volatile("s_waitcnt vmcnt(0)" ::: "memory");
;         } else {
;             XB_SPIN(xb_ld(&bar[XB_XGEN(b.x)]) == gen, bar);
.LBB0_349:
	s_and_b32 s16, s22, 0xff
	s_mov_b64 s[14:15], -1
	s_cmp_lg_u32 s16, 0
	s_mov_b64 s[16:17], -1
	s_sleep 8
	s_cbranch_scc1 .LBB0_353
	v_mov_b64_e32 v[4:5], s[34:35]
	flat_load_dword v0, v[4:5] offset:512 sc1
	s_mov_b64 s[16:17], 0
	s_mov_b64 s[18:19], -1
	s_waitcnt vmcnt(0) lgkmcnt(0)
	v_cmp_eq_u32_e32 vcc, 0, v0
	s_and_saveexec_b64 s[20:21], vcc
	s_cmp_lt_u32 s22, 0x40001
	s_cselect_b64 s[16:17], -1, 0
	s_xor_b64 s[18:19], exec, -1
	s_and_b64 s[16:17], s[16:17], exec
	s_or_b64 exec, exec, s[20:21]

; __device__ __forceinline__ unsigned xb_ld(unsigned* p)              { return __hip_atomic_load(p, __ATOMIC_RELAXED, __HIP_MEMORY_SCOPE_AGENT); }
; __device__ __forceinline__ unsigned xb_add(unsigned* p, unsigned v) { return __hip_atomic_fetch_add(p, v, __ATOMIC_RELAXED, __HIP_MEMORY_SCOPE_AGENT); }
; #define XB_SPIN(cond, bar) do { unsigned _sp = 0; while (cond) { __builtin_amdgcn_s_sleep(1); \
;     if ((++_sp & 255u) == 0u) { if (xb_ld(&(bar)[XB_TMO])) break; if (_sp > XB_SPIN_CAP) { atomicAdd(&(bar)[XB_TMO], 1u); break; } } } } while (0)
; __device__ __forceinline__ void xcd_barrier(const XcdBarrier& b) {
;     ...
;             else XB_SPIN(xb_ld(&bar[XB_TOPGEN]) == tg, bar);
;             __builtin_amdgcn_fence(__ATOMIC_ACQUIRE, "agent");
;             xb_add(&bar[XB_XGEN(b.x)], 1u);
;             asm volatile("s_waitcnt vmcnt(0)" ::: "memory");
;         } else {
;             XB_SPIN(xb_ld(&bar[XB_XGEN(b.x)]) == gen, bar);
.LBB0_363:
	s_and_b32 s18, s26, 0xff
	s_mov_b64 s[16:17], -1
	s_cmp_lg_u32 s18, 0
	s_mov_b64 s[20:21], -1
	s_sleep 8
	s_cbranch_scc0 .LBB0_365
	s_and_saveexec_b64 s[22:23], s[20:21]
	s_cbranch_execz .LBB0_362
	s_branch .LBB0_368

; __device__ __forceinline__ unsigned xb_ld(unsigned* p)              { return __hip_atomic_load(p, __ATOMIC_RELAXED, __HIP_MEMORY_SCOPE_AGENT); }
; __device__ __forceinline__ void xcd_barrier_complete(unsigned* bar, unsigned x, unsigned& nloc, unsigned& nx) {
;     const unsigned G = gridDim.x * gridDim.y * gridDim.z;
;     unsigned sum, cnt, mine, sp = 0u;
;     for (;;) {
;         sum = 0u; cnt = 0u; mine = 0u;
; #pragma unroll
;         for (unsigned j = 0; j < 16; ++j) { const unsigned c = xb_ld(&bar[XB_XCNT(j)]); sum += c; cnt += (c > 0u) ? 1u : 0u; mine = (j == x) ? c : mine; }
;         if (sum == G) break;
;         __builtin_amdgcn_s_sleep(1);
;         if ((++sp & 255u) == 0u) { if (xb_ld(&bar[XB_TMO])) break; if (sp > XB_SPIN_CAP) { atomicAdd(&bar[XB_TMO], 1u); break; } }
;     }
.LBB0_547:
	v_mov_b64_e32 v[12:13], s[38:39]
	flat_load_dword v2, v[12:13] offset:1024 sc1
	s_waitcnt lgkmcnt(0)
	flat_load_dword v0, v[12:13] offset:1280 sc1
	flat_load_dword v3, v[12:13] offset:1536 sc1
	v_readlane_b32 s16, v253, 57
	s_or_b64 s[14:15], s[14:15], exec
	s_or_b64 s[12:13], s[12:13], exec
	s_waitcnt vmcnt(0) lgkmcnt(0)
	v_add_u32_e32 v4, v0, v2
	v_add_u32_e32 v5, v4, v3
	flat_load_dword v4, v[12:13] offset:1792 sc1
	s_waitcnt vmcnt(0) lgkmcnt(0)
	v_add_u32_e32 v6, v5, v4
	flat_load_dword v5, v[12:13] offset:2048 sc1
	s_waitcnt vmcnt(0) lgkmcnt(0)
	v_add_u32_e32 v7, v6, v5
	flat_load_dword v6, v[12:13] offset:2304 sc1
	s_waitcnt vmcnt(0) lgkmcnt(0)
	v_add_u32_e32 v8, v7, v6
	flat_load_dword v7, v[12:13] offset:2560 sc1
	s_waitcnt vmcnt(0) lgkmcnt(0)
	v_add_u32_e32 v9, v8, v7
	flat_load_dword v8, v[12:13] offset:2816 sc1
	s_waitcnt vmcnt(0) lgkmcnt(0)
	v_add_u32_e32 v10, v9, v8
	flat_load_dword v9, v[12:13] offset:3072 sc1
	s_waitcnt vmcnt(0) lgkmcnt(0)
	v_add_u32_e32 v11, v10, v9
	flat_load_dword v10, v[12:13] offset:3328 sc1
	s_waitcnt vmcnt(0) lgkmcnt(0)
	v_add_u32_e32 v14, v11, v10
	flat_load_dword v11, v[12:13] offset:3584 sc1
	s_waitcnt vmcnt(0) lgkmcnt(0)
	v_add_u32_e32 v14, v14, v11
	flat_load_dword v12, v[12:13] offset:3840 sc1
	s_waitcnt vmcnt(0) lgkmcnt(0)
	v_add_u32_e32 v16, v14, v12
	v_mov_b64_e32 v[14:15], s[0:1]
	flat_load_dword v13, v[14:15] sc1
	v_mov_b64_e32 v[14:15], s[2:3]
	flat_load_dword v14, v[14:15] sc1
	s_waitcnt vmcnt(0) lgkmcnt(0)
	v_add_u32_e32 v16, v16, v13
	v_add_u32_e32 v18, v16, v14
	v_mov_b64_e32 v[16:17], s[4:5]
	flat_load_dword v15, v[16:17] sc1
	v_mov_b64_e32 v[16:17], s[6:7]
	flat_load_dword v16, v[16:17] sc1
	s_waitcnt vmcnt(0) lgkmcnt(0)
	v_add_u32_e32 v18, v18, v15
	v_add_u32_e32 v17, v18, v16
	v_cmp_ne_u32_e32 vcc, s16, v17
	s_and_saveexec_b64 s[16:17], vcc
	s_cbranch_execz .LBB0_546
	s_and_b32 s20, s26, 0xff
	s_mov_b64 s[18:19], -1
	s_cmp_eq_u32 s20, 0
	s_mov_b64 s[22:23], -1
	s_mov_b64 s[20:21], -1
	s_sleep 8
	s_cbranch_scc1 .LBB0_550
	s_and_saveexec_b64 s[24:25], s[22:23]
	s_cbranch_execz .LBB0_545
	s_branch .LBB0_553

; __device__ __forceinline__ unsigned xb_ld(unsigned* p)              { return __hip_atomic_load(p, __ATOMIC_RELAXED, __HIP_MEMORY_SCOPE_AGENT); }
; __device__ __forceinline__ unsigned xb_add(unsigned* p, unsigned v) { return __hip_atomic_fetch_add(p, v, __ATOMIC_RELAXED, __HIP_MEMORY_SCOPE_AGENT); }
; #define XB_SPIN(cond, bar) do { unsigned _sp = 0; while (cond) { __builtin_amdgcn_s_sleep(1); \
;     if ((++_sp & 255u) == 0u) { if (xb_ld(&(bar)[XB_TMO])) break; if (_sp > XB_SPIN_CAP) { atomicAdd(&(bar)[XB_TMO], 1u); break; } } } } while (0)
; __device__ __forceinline__ void xcd_barrier(const XcdBarrier& b) {
;     ...
;             else XB_SPIN(xb_ld(&bar[XB_TOPGEN]) == tg, bar);
;             __builtin_amdgcn_fence(__ATOMIC_ACQUIRE, "agent");
;             xb_add(&bar[XB_XGEN(b.x)], 1u);
;             asm volatile("s_waitcnt vmcnt(0)" ::: "memory");
;         } else {
;             XB_SPIN(xb_ld(&bar[XB_XGEN(b.x)]) == gen, bar);
.LBB0_561:
	s_and_b32 s14, s22, 0xff
	s_mov_b64 s[12:13], -1
	s_cmp_lg_u32 s14, 0
	s_mov_b64 s[14:15], -1
	s_sleep 8
	s_cbranch_scc1 .LBB0_565
	v_mov_b64_e32 v[4:5], s[38:39]
	flat_load_dword v0, v[4:5] offset:512 sc1
	s_mov_b64 s[14:15], 0
	s_mov_b64 s[16:17], -1
	s_waitcnt vmcnt(0) lgkmcnt(0)
	v_cmp_eq_u32_e32 vcc, 0, v0
	s_and_saveexec_b64 s[18:19], vcc
	s_cmp_lt_u32 s22, 0x40001
	s_cselect_b64 s[14:15], -1, 0
	s_xor_b64 s[16:17], exec, -1
	s_and_b64 s[14:15], s[14:15], exec
	s_or_b64 exec, exec, s[18:19]

; __device__ __forceinline__ unsigned xb_ld(unsigned* p)              { return __hip_atomic_load(p, __ATOMIC_RELAXED, __HIP_MEMORY_SCOPE_AGENT); }
; __device__ __forceinline__ unsigned xb_add(unsigned* p, unsigned v) { return __hip_atomic_fetch_add(p, v, __ATOMIC_RELAXED, __HIP_MEMORY_SCOPE_AGENT); }
; #define XB_SPIN(cond, bar) do { unsigned _sp = 0; while (cond) { __builtin_amdgcn_s_sleep(1); \
;     if ((++_sp & 255u) == 0u) { if (xb_ld(&(bar)[XB_TMO])) break; if (_sp > XB_SPIN_CAP) { atomicAdd(&(bar)[XB_TMO], 1u); break; } } } } while (0)
; __device__ __forceinline__ void xcd_barrier(const XcdBarrier& b) {
;     ...
;             else XB_SPIN(xb_ld(&bar[XB_TOPGEN]) == tg, bar);
;             __builtin_amdgcn_fence(__ATOMIC_ACQUIRE, "agent");
;             xb_add(&bar[XB_XGEN(b.x)], 1u);
;             asm volatile("s_waitcnt vmcnt(0)" ::: "memory");
;         } else {
;             XB_SPIN(xb_ld(&bar[XB_XGEN(b.x)]) == gen, bar);
.LBB0_575:
	s_and_b32 s14, s22, 0xff
	s_mov_b64 s[12:13], -1
	s_cmp_lg_u32 s14, 0
	s_mov_b64 s[16:17], -1
	s_sleep 8
	s_cbranch_scc0 .LBB0_577
	s_and_saveexec_b64 s[18:19], s[16:17]
	s_cbranch_execz .LBB0_574
	s_branch .LBB0_580

; __device__ __forceinline__ unsigned xb_ld(unsigned* p)              { return __hip_atomic_load(p, __ATOMIC_RELAXED, __HIP_MEMORY_SCOPE_AGENT); }
; __device__ __forceinline__ unsigned xb_add(unsigned* p, unsigned v) { return __hip_atomic_fetch_add(p, v, __ATOMIC_RELAXED, __HIP_MEMORY_SCOPE_AGENT); }
; #define XB_SPIN(cond, bar) do { unsigned _sp = 0; while (cond) { __builtin_amdgcn_s_sleep(1); \
;     if ((++_sp & 255u) == 0u) { if (xb_ld(&(bar)[XB_TMO])) break; if (_sp > XB_SPIN_CAP) { atomicAdd(&(bar)[XB_TMO], 1u); break; } } } } while (0)
; __device__ __forceinline__ void xcd_barrier(const XcdBarrier& b) {
;     ...
;             else XB_SPIN(xb_ld(&bar[XB_TOPGEN]) == tg, bar);
;             __builtin_amdgcn_fence(__ATOMIC_ACQUIRE, "agent");
;             xb_add(&bar[XB_XGEN(b.x)], 1u);
;             asm volatile("s_waitcnt vmcnt(0)" ::: "memory");
;         } else {
;             XB_SPIN(xb_ld(&bar[XB_XGEN(b.x)]) == gen, bar);
.LBB0_610:
	s_and_b32 s14, s20, 0xff
	s_mov_b64 s[12:13], -1
	s_cmp_lg_u32 s14, 0
	s_mov_b64 s[14:15], -1
	s_sleep 8
	s_cbranch_scc1 .LBB0_614
	v_mov_b64_e32 v[4:5], s[38:39]
	flat_load_dword v0, v[4:5] offset:512 sc1
	s_mov_b64 s[14:15], 0
	s_mov_b64 s[16:17], -1
	s_waitcnt vmcnt(0) lgkmcnt(0)
	v_cmp_eq_u32_e32 vcc, 0, v0
	s_and_saveexec_b64 s[18:19], vcc
	s_cmp_lt_u32 s20, 0x40001
	s_cselect_b64 s[14:15], -1, 0
	s_xor_b64 s[16:17], exec, -1
	s_and_b64 s[14:15], s[14:15], exec
	s_or_b64 exec, exec, s[18:19]

; __device__ __forceinline__ unsigned xb_ld(unsigned* p)              { return __hip_atomic_load(p, __ATOMIC_RELAXED, __HIP_MEMORY_SCOPE_AGENT); }
; __device__ __forceinline__ unsigned xb_add(unsigned* p, unsigned v) { return __hip_atomic_fetch_add(p, v, __ATOMIC_RELAXED, __HIP_MEMORY_SCOPE_AGENT); }
; #define XB_SPIN(cond, bar) do { unsigned _sp = 0; while (cond) { __builtin_amdgcn_s_sleep(1); \
;     if ((++_sp & 255u) == 0u) { if (xb_ld(&(bar)[XB_TMO])) break; if (_sp > XB_SPIN_CAP) { atomicAdd(&(bar)[XB_TMO], 1u); break; } } } } while (0)
; __device__ __forceinline__ void xcd_barrier(const XcdBarrier& b) {
;     ...
;             else XB_SPIN(xb_ld(&bar[XB_TOPGEN]) == tg, bar);
;             __builtin_amdgcn_fence(__ATOMIC_ACQUIRE, "agent");
;             xb_add(&bar[XB_XGEN(b.x)], 1u);
;             asm volatile("s_waitcnt vmcnt(0)" ::: "memory");
;         } else {
;             XB_SPIN(xb_ld(&bar[XB_XGEN(b.x)]) == gen, bar);
.LBB0_624:
	s_and_b32 s16, s24, 0xff
	s_mov_b64 s[14:15], -1
	s_cmp_lg_u32 s16, 0
	s_mov_b64 s[18:19], -1
	s_sleep 8
	s_cbranch_scc0 .LBB0_626
	s_and_saveexec_b64 s[20:21], s[18:19]
	s_cbranch_execz .LBB0_623
	s_branch .LBB0_629

; __device__ __forceinline__ unsigned xb_ld(unsigned* p)              { return __hip_atomic_load(p, __ATOMIC_RELAXED, __HIP_MEMORY_SCOPE_AGENT); }
; __device__ __forceinline__ void xcd_barrier_complete(unsigned* bar, unsigned x, unsigned& nloc, unsigned& nx) {
;     const unsigned G = gridDim.x * gridDim.y * gridDim.z;
;     unsigned sum, cnt, mine, sp = 0u;
;     for (;;) {
;         sum = 0u; cnt = 0u; mine = 0u;
; #pragma unroll
;         for (unsigned j = 0; j < 16; ++j) { const unsigned c = xb_ld(&bar[XB_XCNT(j)]); sum += c; cnt += (c > 0u) ? 1u : 0u; mine = (j == x) ? c : mine; }
;         if (sum == G) break;
;         __builtin_amdgcn_s_sleep(1);
;         if ((++sp & 255u) == 0u) { if (xb_ld(&bar[XB_TMO])) break; if (sp > XB_SPIN_CAP) { atomicAdd(&bar[XB_TMO], 1u); break; } }
;     }
.LBB0_1101:
	v_mov_b64_e32 v[12:13], s[36:37]
	flat_load_dword v2, v[12:13] offset:1024 sc1
	s_waitcnt lgkmcnt(0)
	flat_load_dword v0, v[12:13] offset:1280 sc1
	flat_load_dword v3, v[12:13] offset:1536 sc1
	v_readlane_b32 s16, v253, 57
	s_or_b64 s[14:15], s[14:15], exec
	s_or_b64 s[12:13], s[12:13], exec
	s_waitcnt vmcnt(0) lgkmcnt(0)
	v_add_u32_e32 v4, v0, v2
	v_add_u32_e32 v5, v4, v3
	flat_load_dword v4, v[12:13] offset:1792 sc1
	s_waitcnt vmcnt(0) lgkmcnt(0)
	v_add_u32_e32 v6, v5, v4
	flat_load_dword v5, v[12:13] offset:2048 sc1
	s_waitcnt vmcnt(0) lgkmcnt(0)
	v_add_u32_e32 v7, v6, v5
	flat_load_dword v6, v[12:13] offset:2304 sc1
	s_waitcnt vmcnt(0) lgkmcnt(0)
	v_add_u32_e32 v8, v7, v6
	flat_load_dword v7, v[12:13] offset:2560 sc1
	s_waitcnt vmcnt(0) lgkmcnt(0)
	v_add_u32_e32 v9, v8, v7
	flat_load_dword v8, v[12:13] offset:2816 sc1
	s_waitcnt vmcnt(0) lgkmcnt(0)
	v_add_u32_e32 v10, v9, v8
	flat_load_dword v9, v[12:13] offset:3072 sc1
	s_waitcnt vmcnt(0) lgkmcnt(0)
	v_add_u32_e32 v11, v10, v9
	flat_load_dword v10, v[12:13] offset:3328 sc1
	s_waitcnt vmcnt(0) lgkmcnt(0)
	v_add_u32_e32 v14, v11, v10
	flat_load_dword v11, v[12:13] offset:3584 sc1
	s_waitcnt vmcnt(0) lgkmcnt(0)
	v_add_u32_e32 v14, v14, v11
	flat_load_dword v12, v[12:13] offset:3840 sc1
	s_waitcnt vmcnt(0) lgkmcnt(0)
	v_add_u32_e32 v16, v14, v12
	v_mov_b64_e32 v[14:15], s[0:1]
	flat_load_dword v13, v[14:15] sc1
	v_mov_b64_e32 v[14:15], s[2:3]
	flat_load_dword v14, v[14:15] sc1
	s_waitcnt vmcnt(0) lgkmcnt(0)
	v_add_u32_e32 v16, v16, v13
	v_add_u32_e32 v18, v16, v14
	v_mov_b64_e32 v[16:17], s[4:5]
	flat_load_dword v15, v[16:17] sc1
	v_mov_b64_e32 v[16:17], s[6:7]
	flat_load_dword v16, v[16:17] sc1
	s_waitcnt vmcnt(0) lgkmcnt(0)
	v_add_u32_e32 v18, v18, v15
	v_add_u32_e32 v17, v18, v16
	v_cmp_ne_u32_e32 vcc, s16, v17
	s_and_saveexec_b64 s[16:17], vcc
	s_cbranch_execz .LBB0_1100
	s_and_b32 s20, s26, 0xff
	s_mov_b64 s[18:19], -1
	s_cmp_eq_u32 s20, 0
	s_mov_b64 s[22:23], -1
	s_mov_b64 s[20:21], -1
	s_sleep 8
	s_cbranch_scc1 .LBB0_1104
	s_and_saveexec_b64 s[24:25], s[22:23]
	s_cbranch_execz .LBB0_1099
	s_branch .LBB0_1107

; __device__ __forceinline__ unsigned xb_ld(unsigned* p)              { return __hip_atomic_load(p, __ATOMIC_RELAXED, __HIP_MEMORY_SCOPE_AGENT); }
; __device__ __forceinline__ unsigned xb_add(unsigned* p, unsigned v) { return __hip_atomic_fetch_add(p, v, __ATOMIC_RELAXED, __HIP_MEMORY_SCOPE_AGENT); }
; #define XB_SPIN(cond, bar) do { unsigned _sp = 0; while (cond) { __builtin_amdgcn_s_sleep(1); \
;     if ((++_sp & 255u) == 0u) { if (xb_ld(&(bar)[XB_TMO])) break; if (_sp > XB_SPIN_CAP) { atomicAdd(&(bar)[XB_TMO], 1u); break; } } } } while (0)
; __device__ __forceinline__ void xcd_barrier(const XcdBarrier& b) {
;     ...
;             else XB_SPIN(xb_ld(&bar[XB_TOPGEN]) == tg, bar);
;             __builtin_amdgcn_fence(__ATOMIC_ACQUIRE, "agent");
;             xb_add(&bar[XB_XGEN(b.x)], 1u);
;             asm volatile("s_waitcnt vmcnt(0)" ::: "memory");
;         } else {
;             XB_SPIN(xb_ld(&bar[XB_XGEN(b.x)]) == gen, bar);
.LBB0_1115:
	s_and_b32 s14, s22, 0xff
	s_mov_b64 s[12:13], -1
	s_cmp_lg_u32 s14, 0
	s_mov_b64 s[14:15], -1
	s_sleep 8
	s_cbranch_scc1 .LBB0_1119
	v_mov_b64_e32 v[4:5], s[36:37]
	flat_load_dword v0, v[4:5] offset:512 sc1
	s_mov_b64 s[14:15], 0
	s_mov_b64 s[16:17], -1
	s_waitcnt vmcnt(0) lgkmcnt(0)
	v_cmp_eq_u32_e32 vcc, 0, v0
	s_and_saveexec_b64 s[18:19], vcc
	s_cmp_lt_u32 s22, 0x40001
	s_cselect_b64 s[14:15], -1, 0
	s_xor_b64 s[16:17], exec, -1
	s_and_b64 s[14:15], s[14:15], exec
	s_or_b64 exec, exec, s[18:19]

; __device__ __forceinline__ unsigned xb_ld(unsigned* p)              { return __hip_atomic_load(p, __ATOMIC_RELAXED, __HIP_MEMORY_SCOPE_AGENT); }
; __device__ __forceinline__ unsigned xb_add(unsigned* p, unsigned v) { return __hip_atomic_fetch_add(p, v, __ATOMIC_RELAXED, __HIP_MEMORY_SCOPE_AGENT); }
; #define XB_SPIN(cond, bar) do { unsigned _sp = 0; while (cond) { __builtin_amdgcn_s_sleep(1); \
;     if ((++_sp & 255u) == 0u) { if (xb_ld(&(bar)[XB_TMO])) break; if (_sp > XB_SPIN_CAP) { atomicAdd(&(bar)[XB_TMO], 1u); break; } } } } while (0)
; __device__ __forceinline__ void xcd_barrier(const XcdBarrier& b) {
;     ...
;             else XB_SPIN(xb_ld(&bar[XB_TOPGEN]) == tg, bar);
;             __builtin_amdgcn_fence(__ATOMIC_ACQUIRE, "agent");
;             xb_add(&bar[XB_XGEN(b.x)], 1u);
;             asm volatile("s_waitcnt vmcnt(0)" ::: "memory");
;         } else {
;             XB_SPIN(xb_ld(&bar[XB_XGEN(b.x)]) == gen, bar);
.LBB0_1372:
	s_and_b32 s14, s20, 0xff
	s_mov_b64 s[12:13], -1
	s_cmp_lg_u32 s14, 0
	s_mov_b64 s[14:15], -1
	s_sleep 8
	s_cbranch_scc1 .LBB0_1376
	v_mov_b64_e32 v[4:5], s[36:37]
	flat_load_dword v0, v[4:5] offset:512 sc1
	s_mov_b64 s[14:15], 0
	s_mov_b64 s[16:17], -1
	s_waitcnt vmcnt(0) lgkmcnt(0)
	v_cmp_eq_u32_e32 vcc, 0, v0
	s_and_saveexec_b64 s[18:19], vcc
	s_cmp_lt_u32 s20, 0x40001
	s_cselect_b64 s[14:15], -1, 0
	s_xor_b64 s[16:17], exec, -1
	s_and_b64 s[14:15], s[14:15], exec
	s_or_b64 exec, exec, s[18:19]
